# conv rewritten (chunk-column per wave, 4 rows in flight); ctx split-K partial-sum loop batched; plus earlier final-norm/adaLN/epilogue edits
# speedup vs baseline: 1.0106x; 1.0106x over previous
; __global__ void __launch_bounds__(512, 2) fwd_kernel(const Args a) {
;     ...
;                 const int mend = (l == DEPTH - 1) ? ML : MT;
;                 const float* cw = conv_w + l * 3 * D; const float* cbias = conv_b + l * D;
;                 for (int m = gw; m < mend; m += NGW) {
;                     const bool lat = m < ML; const int t = lat ? (m & (SEQ - 1)) : ((m - ML) & (CTXL - 1)); const int tl = lat ? SEQ - 1 : CTXL - 1;
;                     const bool hp = t > 0, hn = t < tl;
; #pragma unroll
;                     for (int j = 0; j < 4; ++j) {
;                         const int c0 = (64 * j + lane) * 8; const size_t o = (size_t)m * D + c0;
;                         const u32x4 zz = (u32x4){0u, 0u, 0u, 0u};
;                         const u32x4 up = hp ? *(const u32x4*)(Ub + o - D) : zz, uc = *(const u32x4*)(Ub + o), un = hn ? *(const u32x4*)(Ub + o + D) : zz, cb = *(const u32x4*)(CBb + o);
;                         const f32x4 w0a = *(const f32x4*)(cw + c0), w0b = *(const f32x4*)(cw + c0 + 4), w1a = *(const f32x4*)(cw + D + c0), w1b = *(const f32x4*)(cw + D + c0 + 4);
;                         const f32x4 w2a = *(const f32x4*)(cw + 2 * D + c0), w2b = *(const f32x4*)(cw + 2 * D + c0 + 4), ba = *(const f32x4*)(cbias + c0), bb = *(const f32x4*)(cbias + c0 + 4);
.LBB0_359:
	s_and_b64 s[0:1], s[0:1], exec
	s_movk_i32 s0, 0x4200
	s_cselect_b32 s2, 0x4000, s0
	v_readlane_b32 s0, v255, 19
	s_cmp_ge_i32 s0, s2
	v_readlane_b32 s1, v255, 20
	s_cbranch_scc1 .LBB0_379
	s_lshl_b32 s0, s65, 11
	s_ashr_i32 s1, s0, 31
	s_mov_b32 s4, s64
	s_mov_b64 s[10:11], s[66:67]
	s_mov_b32 s8, s65
	s_mov_b32 s9, s68
	s_mov_b32 s12, s69
	s_mov_b32 s13, s70
	s_mov_b64 s[14:15], s[72:73]
	v_readlane_b32 s64, v255, 2
	s_lshl_b64 s[0:1], s[0:1], 2
	v_readlane_b32 s65, v255, 3
	v_readlane_b32 s68, v255, 6
	v_readlane_b32 s69, v255, 7
	s_mov_b32 s65, s8
	s_add_u32 s0, s68, s0
	s_mulk_i32 s8, 0x1800
	s_mov_b32 s68, s9
	s_addc_u32 s1, s69, s1
	s_ashr_i32 s9, s8, 31
	v_readlane_b32 s66, v255, 4
	s_lshl_b64 s[8:9], s[8:9], 2
	v_readlane_b32 s67, v255, 5
	s_add_u32 s8, s66, s8
	s_addc_u32 s9, s67, s9
	s_mov_b64 s[66:67], s[10:11]
	s_add_u32 s10, s8, 0x2000
	s_addc_u32 s11, s9, 0
	v_readlane_b32 s70, v255, 8
	s_mov_b32 s69, s12
	s_add_u32 s12, s8, 0x4000
	v_lshlrev_b32_e32 v176, 5, v188
	s_mov_b32 s70, s13
	s_addc_u32 s13, s9, 0
	v_or_b32_e32 v0, 0x800, v176
	v_mov_b32_e32 v1, v177
	v_lshl_add_u64 v[16:17], s[8:9], 0, v[176:177]
	v_lshl_add_u64 v[18:19], s[10:11], 0, v[176:177]
	v_lshl_add_u64 v[20:21], s[12:13], 0, v[176:177]
	v_lshl_add_u64 v[22:23], s[0:1], 0, v[176:177]
	v_lshl_add_u64 v[24:25], s[10:11], 0, v[0:1]
	v_lshl_add_u64 v[26:27], s[12:13], 0, v[0:1]
	v_or_b32_e32 v0, 0x1000, v176
	v_or_b32_e32 v176, 0x1800, v176
	v_lshl_add_u64 v[34:35], s[0:1], 0, v[0:1]
	v_lshl_add_u64 v[42:43], s[0:1], 0, v[176:177]
	v_readlane_b32 s0, v254, 49
	v_lshl_add_u64 v[36:37], s[8:9], 0, v[176:177]
	v_lshl_add_u64 v[38:39], s[10:11], 0, v[176:177]
	v_lshl_add_u64 v[40:41], s[12:13], 0, v[176:177]
	v_lshlrev_b32_e32 v176, 4, v188
	v_readlane_b32 s1, v254, 50
	v_readlane_b32 s72, v255, 10
	v_readlane_b32 s73, v255, 11
	v_lshl_add_u64 v[44:45], s[0:1], 0, v[176:177]
	v_readlane_b32 s0, v255, 19
	s_mov_b64 s[72:73], s[14:15]
	s_mov_b32 s64, s4
	v_lshl_add_u64 v[28:29], s[8:9], 0, v[0:1]
	v_lshl_add_u64 v[30:31], s[10:11], 0, v[0:1]
	v_lshl_add_u64 v[32:33], s[12:13], 0, v[0:1]
	s_mov_b32 s4, s0
	v_readlane_b32 s71, v255, 9
	v_readlane_b32 s74, v255, 12
	v_readlane_b32 s75, v255, 13
	v_readlane_b32 s76, v255, 14
	v_readlane_b32 s77, v255, 15
	v_readlane_b32 s78, v255, 16
	v_readlane_b32 s79, v255, 17
	v_readlane_b32 s1, v255, 20
	v_readlane_b32 s0, v255, 19
	s_and_b32 s1, s0, 3
	s_lshr_b32 s4, s0, 2
	s_lshl_b32 s14, s1, 11
	s_mov_b32 s15, 0
	v_lshl_add_u64 v[16:17], v[16:17], 0, s[14:15]
	v_lshl_add_u64 v[18:19], v[18:19], 0, s[14:15]
	v_lshl_add_u64 v[20:21], v[20:21], 0, s[14:15]
	v_lshl_add_u64 v[22:23], v[22:23], 0, s[14:15]
	global_load_dwordx4 v[128:131], v[16:17], off
	global_load_dwordx4 v[132:135], v[16:17], off offset:16
	global_load_dwordx4 v[136:139], v[18:19], off
	global_load_dwordx4 v[140:143], v[18:19], off offset:16
	global_load_dwordx4 v[144:147], v[20:21], off
	global_load_dwordx4 v[148:151], v[20:21], off offset:16
	global_load_dwordx4 v[152:155], v[22:23], off
	global_load_dwordx4 v[156:159], v[22:23], off offset:16
	v_readlane_b32 s8, v254, 49
	v_readlane_b32 s9, v254, 50
	s_lshl_b32 s10, s0, 12
	s_sub_u32 s8, s8, s10
	s_subb_u32 s9, s9, 0
	s_sub_u32 s8, s8, 0x1c00
	s_subb_u32 s9, s9, 0
	s_lshl_b32 s10, s4, 12
	s_lshl_b32 s11, s1, 10
	s_add_u32 s10, s10, s11
	s_add_u32 s8, s8, s10
	s_addc_u32 s9, s9, 0
	v_lshlrev_b32_e32 v0, 4, v188
	v_mov_b32_e32 v1, 0
	v_lshl_add_u64 v[160:161], s[8:9], 0, v[0:1]
	s_sub_u32 s10, s8, 0x4200000
	s_subb_u32 s11, s9, 0
	v_lshl_add_u64 v[164:165], s[10:11], 0, v[0:1]
	v_mov_b32_e32 v166, v164
	v_mov_b32_e32 v167, v165
	s_mov_b64 s[14:15], 0x1000
	v_lshl_add_u64 v[162:163], v[160:161], 0, s[14:15]
	s_mov_b32 s14, 0x200000
	s_mov_b32 s15, 0
	global_load_dwordx4 v[64:67], v[160:161], off offset:-4096
	global_load_dwordx4 v[68:71], v[160:161], off
	global_load_dwordx4 v[72:75], v[162:163], off
	global_load_dwordx4 v[76:79], v[164:165], off
	v_lshl_add_u64 v[160:161], v[160:161], 0, s[14:15]
	v_lshl_add_u64 v[162:163], v[162:163], 0, s[14:15]
	v_lshl_add_u64 v[164:165], v[164:165], 0, s[14:15]
	global_load_dwordx4 v[80:83], v[160:161], off offset:-4096
	global_load_dwordx4 v[84:87], v[160:161], off
	global_load_dwordx4 v[88:91], v[162:163], off
	global_load_dwordx4 v[92:95], v[164:165], off
	v_lshl_add_u64 v[160:161], v[160:161], 0, s[14:15]
	v_lshl_add_u64 v[162:163], v[162:163], 0, s[14:15]
	v_lshl_add_u64 v[164:165], v[164:165], 0, s[14:15]
	global_load_dwordx4 v[96:99], v[160:161], off offset:-4096
	global_load_dwordx4 v[100:103], v[160:161], off
	global_load_dwordx4 v[104:107], v[162:163], off
	global_load_dwordx4 v[108:111], v[164:165], off
	v_lshl_add_u64 v[160:161], v[160:161], 0, s[14:15]
	v_lshl_add_u64 v[162:163], v[162:163], 0, s[14:15]
	v_lshl_add_u64 v[164:165], v[164:165], 0, s[14:15]
	global_load_dwordx4 v[112:115], v[160:161], off offset:-4096
	global_load_dwordx4 v[116:119], v[160:161], off
	global_load_dwordx4 v[120:123], v[162:163], off
	global_load_dwordx4 v[124:127], v[164:165], off
	v_lshl_add_u64 v[160:161], v[160:161], 0, s[14:15]
	v_lshl_add_u64 v[162:163], v[162:163], 0, s[14:15]
	v_lshl_add_u64 v[164:165], v[164:165], 0, s[14:15]
.Lcv_loop:
	s_cmp_ge_u32 s4, s2
	s_cbranch_scc1 .Lcv_done
	s_movk_i32 s9, 0xff
	s_cmpk_lt_u32 s4, 0x4000
	s_cselect_b32 s8, 0x1fff, s9
	s_and_b32 s9, s4, s8
	s_waitcnt vmcnt(12)
	s_cmp_lg_u32 s9, 0
	s_cbranch_scc1 .Lcv_hp0
	v_mov_b32_e32 v64, 0
	v_mov_b32_e32 v65, 0
	v_mov_b32_e32 v66, 0
	v_mov_b32_e32 v67, 0
.Lcv_hp0:
	s_cmp_lg_u32 s9, s8
	s_cbranch_scc1 .Lcv_hn0
	v_mov_b32_e32 v72, 0
	v_mov_b32_e32 v73, 0
	v_mov_b32_e32 v74, 0
	v_mov_b32_e32 v75, 0
; __device__ __forceinline__ u32x4 pack8(const f32x4 a, const f32x4 b) { u32x4 w; w.x = cvt_pk_bf16(a[0], a[1]); w.y = cvt_pk_bf16(a[2], a[3]); w.z = cvt_pk_bf16(b[0], b[1]); w.w = cvt_pk_bf16(b[2], b[3]); return w; }
; #define UNPK_LO(q) ((f32x4){bf_lo(q.x), bf_hi(q.x), bf_lo(q.y), bf_hi(q.y)})
; #define UNPK_HI(q) ((f32x4){bf_lo(q.z), bf_hi(q.z), bf_lo(q.w), bf_hi(q.w)})
; __global__ void __launch_bounds__(512, 2) fwd_kernel(const Args a) {
;     ...
;                 for (int m = gw; m < mend; m += NGW) {
;                     const bool lat = m < ML; const int t = lat ? (m & (SEQ - 1)) : ((m - ML) & (CTXL - 1)); const int tl = lat ? SEQ - 1 : CTXL - 1;
;                     const bool hp = t > 0, hn = t < tl;
; #pragma unroll
;                     for (int j = 0; j < 4; ++j) {
;                         const int c0 = (64 * j + lane) * 8; const size_t o = (size_t)m * D + c0;
;                         const u32x4 zz = (u32x4){0u, 0u, 0u, 0u};
;                         const u32x4 up = hp ? *(const u32x4*)(Ub + o - D) : zz, uc = *(const u32x4*)(Ub + o), un = hn ? *(const u32x4*)(Ub + o + D) : zz, cb = *(const u32x4*)(CBb + o);
;                         const f32x4 w0a = *(const f32x4*)(cw + c0), w0b = *(const f32x4*)(cw + c0 + 4), w1a = *(const f32x4*)(cw + D + c0), w1b = *(const f32x4*)(cw + D + c0 + 4);
;                         const f32x4 w2a = *(const f32x4*)(cw + 2 * D + c0), w2b = *(const f32x4*)(cw + 2 * D + c0 + 4), ba = *(const f32x4*)(cbias + c0), bb = *(const f32x4*)(cbias + c0 + 4);
;     ...
;                         const f32x4 ya = UNPK_LO(cb) * (w0a * UNPK_LO(up) + w1a * UNPK_LO(uc) + w2a * UNPK_LO(un) + ba);
;                         const f32x4 yb = UNPK_HI(cb) * (w0b * UNPK_HI(up) + w1b * UNPK_HI(uc) + w2b * UNPK_HI(un) + bb);
;     ...
;                         *(u32x4*)(CBb + o) = pack8(ya, yb);
;                     }
.Lcv_hn0:
	v_lshlrev_b32_e32 v0, 16, v64
	v_and_b32_e32 v1, 0xffff0000, v64
	v_lshlrev_b32_e32 v2, 16, v65
	v_and_b32_e32 v3, 0xffff0000, v65
	v_lshlrev_b32_e32 v4, 16, v66
	v_and_b32_e32 v5, 0xffff0000, v66
	v_lshlrev_b32_e32 v6, 16, v67
	v_and_b32_e32 v7, 0xffff0000, v67
	v_lshlrev_b32_e32 v8, 16, v68
	v_and_b32_e32 v9, 0xffff0000, v68
	v_lshlrev_b32_e32 v10, 16, v69
	v_and_b32_e32 v11, 0xffff0000, v69
	v_lshlrev_b32_e32 v12, 16, v70
	v_and_b32_e32 v13, 0xffff0000, v70
	v_lshlrev_b32_e32 v14, 16, v71
	v_and_b32_e32 v15, 0xffff0000, v71
	v_lshlrev_b32_e32 v16, 16, v72
	v_and_b32_e32 v17, 0xffff0000, v72
	v_lshlrev_b32_e32 v18, 16, v73
	v_and_b32_e32 v19, 0xffff0000, v73
	v_lshlrev_b32_e32 v20, 16, v74
	v_and_b32_e32 v21, 0xffff0000, v74
	v_lshlrev_b32_e32 v22, 16, v75
	v_and_b32_e32 v23, 0xffff0000, v75
	v_lshlrev_b32_e32 v24, 16, v76
	v_and_b32_e32 v25, 0xffff0000, v76
	v_lshlrev_b32_e32 v26, 16, v77
	v_and_b32_e32 v27, 0xffff0000, v77
	v_lshlrev_b32_e32 v28, 16, v78
	v_and_b32_e32 v29, 0xffff0000, v78
	v_lshlrev_b32_e32 v30, 16, v79
	v_and_b32_e32 v31, 0xffff0000, v79
	global_load_dwordx4 v[64:67], v[160:161], off offset:-4096
	global_load_dwordx4 v[68:71], v[160:161], off
	global_load_dwordx4 v[72:75], v[162:163], off
	global_load_dwordx4 v[76:79], v[164:165], off
	v_lshl_add_u64 v[160:161], v[160:161], 0, s[14:15]
	v_lshl_add_u64 v[162:163], v[162:163], 0, s[14:15]
	v_lshl_add_u64 v[164:165], v[164:165], 0, s[14:15]
	v_pk_mul_f32 v[48:49], v[136:137], v[8:9]
	v_pk_fma_f32 v[48:49], v[128:129], v[0:1], v[48:49]
	v_pk_fma_f32 v[48:49], v[144:145], v[16:17], v[48:49]
	v_pk_add_f32 v[48:49], v[152:153], v[48:49]
	v_pk_mul_f32 v[56:57], v[48:49], v[24:25]
	v_pk_mul_f32 v[50:51], v[138:139], v[10:11]
	v_pk_fma_f32 v[50:51], v[130:131], v[2:3], v[50:51]
	v_pk_fma_f32 v[50:51], v[146:147], v[18:19], v[50:51]
	v_pk_add_f32 v[50:51], v[154:155], v[50:51]
	v_pk_mul_f32 v[58:59], v[50:51], v[26:27]
	v_pk_mul_f32 v[52:53], v[140:141], v[12:13]
	v_pk_fma_f32 v[52:53], v[132:133], v[4:5], v[52:53]
	v_pk_fma_f32 v[52:53], v[148:149], v[20:21], v[52:53]
	v_pk_add_f32 v[52:53], v[156:157], v[52:53]
	v_pk_mul_f32 v[60:61], v[52:53], v[28:29]
	v_pk_mul_f32 v[54:55], v[142:143], v[14:15]
	v_pk_fma_f32 v[54:55], v[134:135], v[6:7], v[54:55]
	v_pk_fma_f32 v[54:55], v[150:151], v[22:23], v[54:55]
	v_pk_add_f32 v[54:55], v[158:159], v[54:55]
	v_pk_mul_f32 v[62:63], v[54:55], v[30:31]
	v_cvt_pk_bf16_f32 v32, v56, v57
	v_cvt_pk_bf16_f32 v33, v58, v59
	v_cvt_pk_bf16_f32 v34, v60, v61
	v_cvt_pk_bf16_f32 v35, v62, v63
	global_store_dwordx4 v[166:167], v[32:35], off
	v_lshl_add_u64 v[166:167], v[166:167], 0, s[14:15]
	s_addk_i32 s4, 0x200
	s_cmp_ge_u32 s4, s2
	s_cbranch_scc1 .Lcv_done
	s_movk_i32 s9, 0xff
	s_cmpk_lt_u32 s4, 0x4000
	s_cselect_b32 s8, 0x1fff, s9
	s_and_b32 s9, s4, s8
	s_waitcnt vmcnt(12)
	s_cmp_lg_u32 s9, 0
	s_cbranch_scc1 .Lcv_hp1
	v_mov_b32_e32 v80, 0
	v_mov_b32_e32 v81, 0
	v_mov_b32_e32 v82, 0
	v_mov_b32_e32 v83, 0
.Lcv_hp1:
	s_cmp_lg_u32 s9, s8
	s_cbranch_scc1 .Lcv_hn1
	v_mov_b32_e32 v88, 0
	v_mov_b32_e32 v89, 0
	v_mov_b32_e32 v90, 0
	v_mov_b32_e32 v91, 0
.Lcv_hn1:
	v_lshlrev_b32_e32 v0, 16, v80
	v_and_b32_e32 v1, 0xffff0000, v80
	v_lshlrev_b32_e32 v2, 16, v81
	v_and_b32_e32 v3, 0xffff0000, v81
	v_lshlrev_b32_e32 v4, 16, v82
	v_and_b32_e32 v5, 0xffff0000, v82
	v_lshlrev_b32_e32 v6, 16, v83
	v_and_b32_e32 v7, 0xffff0000, v83
	v_lshlrev_b32_e32 v8, 16, v84
	v_and_b32_e32 v9, 0xffff0000, v84
	v_lshlrev_b32_e32 v10, 16, v85
	v_and_b32_e32 v11, 0xffff0000, v85
	v_lshlrev_b32_e32 v12, 16, v86
	v_and_b32_e32 v13, 0xffff0000, v86
	v_lshlrev_b32_e32 v14, 16, v87
	v_and_b32_e32 v15, 0xffff0000, v87
	v_lshlrev_b32_e32 v16, 16, v88
	v_and_b32_e32 v17, 0xffff0000, v88
	v_lshlrev_b32_e32 v18, 16, v89
	v_and_b32_e32 v19, 0xffff0000, v89
	v_lshlrev_b32_e32 v20, 16, v90
	v_and_b32_e32 v21, 0xffff0000, v90
	v_lshlrev_b32_e32 v22, 16, v91
	v_and_b32_e32 v23, 0xffff0000, v91
	v_lshlrev_b32_e32 v24, 16, v92
	v_and_b32_e32 v25, 0xffff0000, v92
	v_lshlrev_b32_e32 v26, 16, v93
	v_and_b32_e32 v27, 0xffff0000, v93
	v_lshlrev_b32_e32 v28, 16, v94
	v_and_b32_e32 v29, 0xffff0000, v94
	v_lshlrev_b32_e32 v30, 16, v95
	v_and_b32_e32 v31, 0xffff0000, v95
	global_load_dwordx4 v[80:83], v[160:161], off offset:-4096
	global_load_dwordx4 v[84:87], v[160:161], off
	global_load_dwordx4 v[88:91], v[162:163], off
	global_load_dwordx4 v[92:95], v[164:165], off
	v_lshl_add_u64 v[160:161], v[160:161], 0, s[14:15]
	v_lshl_add_u64 v[162:163], v[162:163], 0, s[14:15]
	v_lshl_add_u64 v[164:165], v[164:165], 0, s[14:15]
	v_pk_mul_f32 v[48:49], v[136:137], v[8:9]
	v_pk_fma_f32 v[48:49], v[128:129], v[0:1], v[48:49]
	v_pk_fma_f32 v[48:49], v[144:145], v[16:17], v[48:49]
	v_pk_add_f32 v[48:49], v[152:153], v[48:49]
	v_pk_mul_f32 v[56:57], v[48:49], v[24:25]
	v_pk_mul_f32 v[50:51], v[138:139], v[10:11]
	v_pk_fma_f32 v[50:51], v[130:131], v[2:3], v[50:51]
	v_pk_fma_f32 v[50:51], v[146:147], v[18:19], v[50:51]
	v_pk_add_f32 v[50:51], v[154:155], v[50:51]
	v_pk_mul_f32 v[58:59], v[50:51], v[26:27]
	v_pk_mul_f32 v[52:53], v[140:141], v[12:13]
	v_pk_fma_f32 v[52:53], v[132:133], v[4:5], v[52:53]
	v_pk_fma_f32 v[52:53], v[148:149], v[20:21], v[52:53]
	v_pk_add_f32 v[52:53], v[156:157], v[52:53]
	v_pk_mul_f32 v[60:61], v[52:53], v[28:29]
	v_pk_mul_f32 v[54:55], v[142:143], v[14:15]
	v_pk_fma_f32 v[54:55], v[134:135], v[6:7], v[54:55]
	v_pk_fma_f32 v[54:55], v[150:151], v[22:23], v[54:55]
	v_pk_add_f32 v[54:55], v[158:159], v[54:55]
	v_pk_mul_f32 v[62:63], v[54:55], v[30:31]
	v_cvt_pk_bf16_f32 v36, v56, v57
	v_cvt_pk_bf16_f32 v37, v58, v59
	v_cvt_pk_bf16_f32 v38, v60, v61
	v_cvt_pk_bf16_f32 v39, v62, v63
	global_store_dwordx4 v[166:167], v[36:39], off
	v_lshl_add_u64 v[166:167], v[166:167], 0, s[14:15]
	s_addk_i32 s4, 0x200
	s_cmp_ge_u32 s4, s2
	s_cbranch_scc1 .Lcv_done
	s_movk_i32 s9, 0xff
	s_cmpk_lt_u32 s4, 0x4000
	s_cselect_b32 s8, 0x1fff, s9
	s_and_b32 s9, s4, s8
	s_waitcnt vmcnt(12)
	s_cmp_lg_u32 s9, 0
	s_cbranch_scc1 .Lcv_hp2
	v_mov_b32_e32 v96, 0
	v_mov_b32_e32 v97, 0
	v_mov_b32_e32 v98, 0
	v_mov_b32_e32 v99, 0
; __device__ __forceinline__ u32x4 pack8(const f32x4 a, const f32x4 b) { u32x4 w; w.x = cvt_pk_bf16(a[0], a[1]); w.y = cvt_pk_bf16(a[2], a[3]); w.z = cvt_pk_bf16(b[0], b[1]); w.w = cvt_pk_bf16(b[2], b[3]); return w; }
; #define UNPK_LO(q) ((f32x4){bf_lo(q.x), bf_hi(q.x), bf_lo(q.y), bf_hi(q.y)})
; #define UNPK_HI(q) ((f32x4){bf_lo(q.z), bf_hi(q.z), bf_lo(q.w), bf_hi(q.w)})
; __global__ void __launch_bounds__(512, 2) fwd_kernel(const Args a) {
;     ...
;                 for (int m = gw; m < mend; m += NGW) {
;                     const bool lat = m < ML; const int t = lat ? (m & (SEQ - 1)) : ((m - ML) & (CTXL - 1)); const int tl = lat ? SEQ - 1 : CTXL - 1;
;                     const bool hp = t > 0, hn = t < tl;
; #pragma unroll
;                     for (int j = 0; j < 4; ++j) {
;                         const int c0 = (64 * j + lane) * 8; const size_t o = (size_t)m * D + c0;
;                         const u32x4 zz = (u32x4){0u, 0u, 0u, 0u};
;                         const u32x4 up = hp ? *(const u32x4*)(Ub + o - D) : zz, uc = *(const u32x4*)(Ub + o), un = hn ? *(const u32x4*)(Ub + o + D) : zz, cb = *(const u32x4*)(CBb + o);
;                         const f32x4 w0a = *(const f32x4*)(cw + c0), w0b = *(const f32x4*)(cw + c0 + 4), w1a = *(const f32x4*)(cw + D + c0), w1b = *(const f32x4*)(cw + D + c0 + 4);
;                         const f32x4 w2a = *(const f32x4*)(cw + 2 * D + c0), w2b = *(const f32x4*)(cw + 2 * D + c0 + 4), ba = *(const f32x4*)(cbias + c0), bb = *(const f32x4*)(cbias + c0 + 4);
;     ...
;                         const f32x4 ya = UNPK_LO(cb) * (w0a * UNPK_LO(up) + w1a * UNPK_LO(uc) + w2a * UNPK_LO(un) + ba);
;                         const f32x4 yb = UNPK_HI(cb) * (w0b * UNPK_HI(up) + w1b * UNPK_HI(uc) + w2b * UNPK_HI(un) + bb);
;     ...
;                         *(u32x4*)(CBb + o) = pack8(ya, yb);
;                     }
;                 }
.Lcv_hp2:
	s_cmp_lg_u32 s9, s8
	s_cbranch_scc1 .Lcv_hn2
	v_mov_b32_e32 v104, 0
	v_mov_b32_e32 v105, 0
	v_mov_b32_e32 v106, 0
	v_mov_b32_e32 v107, 0
.Lcv_hn2:
	v_lshlrev_b32_e32 v0, 16, v96
	v_and_b32_e32 v1, 0xffff0000, v96
	v_lshlrev_b32_e32 v2, 16, v97
	v_and_b32_e32 v3, 0xffff0000, v97
	v_lshlrev_b32_e32 v4, 16, v98
	v_and_b32_e32 v5, 0xffff0000, v98
	v_lshlrev_b32_e32 v6, 16, v99
	v_and_b32_e32 v7, 0xffff0000, v99
	v_lshlrev_b32_e32 v8, 16, v100
	v_and_b32_e32 v9, 0xffff0000, v100
	v_lshlrev_b32_e32 v10, 16, v101
	v_and_b32_e32 v11, 0xffff0000, v101
	v_lshlrev_b32_e32 v12, 16, v102
	v_and_b32_e32 v13, 0xffff0000, v102
	v_lshlrev_b32_e32 v14, 16, v103
	v_and_b32_e32 v15, 0xffff0000, v103
	v_lshlrev_b32_e32 v16, 16, v104
	v_and_b32_e32 v17, 0xffff0000, v104
	v_lshlrev_b32_e32 v18, 16, v105
	v_and_b32_e32 v19, 0xffff0000, v105
	v_lshlrev_b32_e32 v20, 16, v106
	v_and_b32_e32 v21, 0xffff0000, v106
	v_lshlrev_b32_e32 v22, 16, v107
	v_and_b32_e32 v23, 0xffff0000, v107
	v_lshlrev_b32_e32 v24, 16, v108
	v_and_b32_e32 v25, 0xffff0000, v108
	v_lshlrev_b32_e32 v26, 16, v109
	v_and_b32_e32 v27, 0xffff0000, v109
	v_lshlrev_b32_e32 v28, 16, v110
	v_and_b32_e32 v29, 0xffff0000, v110
	v_lshlrev_b32_e32 v30, 16, v111
	v_and_b32_e32 v31, 0xffff0000, v111
	global_load_dwordx4 v[96:99], v[160:161], off offset:-4096
	global_load_dwordx4 v[100:103], v[160:161], off
	global_load_dwordx4 v[104:107], v[162:163], off
	global_load_dwordx4 v[108:111], v[164:165], off
	v_lshl_add_u64 v[160:161], v[160:161], 0, s[14:15]
	v_lshl_add_u64 v[162:163], v[162:163], 0, s[14:15]
	v_lshl_add_u64 v[164:165], v[164:165], 0, s[14:15]
	v_pk_mul_f32 v[48:49], v[136:137], v[8:9]
	v_pk_fma_f32 v[48:49], v[128:129], v[0:1], v[48:49]
	v_pk_fma_f32 v[48:49], v[144:145], v[16:17], v[48:49]
	v_pk_add_f32 v[48:49], v[152:153], v[48:49]
	v_pk_mul_f32 v[56:57], v[48:49], v[24:25]
	v_pk_mul_f32 v[50:51], v[138:139], v[10:11]
	v_pk_fma_f32 v[50:51], v[130:131], v[2:3], v[50:51]
	v_pk_fma_f32 v[50:51], v[146:147], v[18:19], v[50:51]
	v_pk_add_f32 v[50:51], v[154:155], v[50:51]
	v_pk_mul_f32 v[58:59], v[50:51], v[26:27]
	v_pk_mul_f32 v[52:53], v[140:141], v[12:13]
	v_pk_fma_f32 v[52:53], v[132:133], v[4:5], v[52:53]
	v_pk_fma_f32 v[52:53], v[148:149], v[20:21], v[52:53]
	v_pk_add_f32 v[52:53], v[156:157], v[52:53]
	v_pk_mul_f32 v[60:61], v[52:53], v[28:29]
	v_pk_mul_f32 v[54:55], v[142:143], v[14:15]
	v_pk_fma_f32 v[54:55], v[134:135], v[6:7], v[54:55]
	v_pk_fma_f32 v[54:55], v[150:151], v[22:23], v[54:55]
	v_pk_add_f32 v[54:55], v[158:159], v[54:55]
	v_pk_mul_f32 v[62:63], v[54:55], v[30:31]
	v_cvt_pk_bf16_f32 v40, v56, v57
	v_cvt_pk_bf16_f32 v41, v58, v59
	v_cvt_pk_bf16_f32 v42, v60, v61
	v_cvt_pk_bf16_f32 v43, v62, v63
	global_store_dwordx4 v[166:167], v[40:43], off
	v_lshl_add_u64 v[166:167], v[166:167], 0, s[14:15]
	s_addk_i32 s4, 0x200
	s_cmp_ge_u32 s4, s2
	s_cbranch_scc1 .Lcv_done
	s_movk_i32 s9, 0xff
	s_cmpk_lt_u32 s4, 0x4000
	s_cselect_b32 s8, 0x1fff, s9
	s_and_b32 s9, s4, s8
	s_waitcnt vmcnt(12)
	s_cmp_lg_u32 s9, 0
	s_cbranch_scc1 .Lcv_hp3
	v_mov_b32_e32 v112, 0
	v_mov_b32_e32 v113, 0
	v_mov_b32_e32 v114, 0
	v_mov_b32_e32 v115, 0
.Lcv_hp3:
	s_cmp_lg_u32 s9, s8
	s_cbranch_scc1 .Lcv_hn3
	v_mov_b32_e32 v120, 0
	v_mov_b32_e32 v121, 0
	v_mov_b32_e32 v122, 0
	v_mov_b32_e32 v123, 0
.Lcv_hn3:
	v_lshlrev_b32_e32 v0, 16, v112
	v_and_b32_e32 v1, 0xffff0000, v112
	v_lshlrev_b32_e32 v2, 16, v113
	v_and_b32_e32 v3, 0xffff0000, v113
	v_lshlrev_b32_e32 v4, 16, v114
	v_and_b32_e32 v5, 0xffff0000, v114
	v_lshlrev_b32_e32 v6, 16, v115
	v_and_b32_e32 v7, 0xffff0000, v115
	v_lshlrev_b32_e32 v8, 16, v116
	v_and_b32_e32 v9, 0xffff0000, v116
	v_lshlrev_b32_e32 v10, 16, v117
	v_and_b32_e32 v11, 0xffff0000, v117
	v_lshlrev_b32_e32 v12, 16, v118
	v_and_b32_e32 v13, 0xffff0000, v118
	v_lshlrev_b32_e32 v14, 16, v119
	v_and_b32_e32 v15, 0xffff0000, v119
	v_lshlrev_b32_e32 v16, 16, v120
	v_and_b32_e32 v17, 0xffff0000, v120
	v_lshlrev_b32_e32 v18, 16, v121
	v_and_b32_e32 v19, 0xffff0000, v121
	v_lshlrev_b32_e32 v20, 16, v122
	v_and_b32_e32 v21, 0xffff0000, v122
	v_lshlrev_b32_e32 v22, 16, v123
	v_and_b32_e32 v23, 0xffff0000, v123
	v_lshlrev_b32_e32 v24, 16, v124
	v_and_b32_e32 v25, 0xffff0000, v124
	v_lshlrev_b32_e32 v26, 16, v125
	v_and_b32_e32 v27, 0xffff0000, v125
	v_lshlrev_b32_e32 v28, 16, v126
	v_and_b32_e32 v29, 0xffff0000, v126
	v_lshlrev_b32_e32 v30, 16, v127
	v_and_b32_e32 v31, 0xffff0000, v127
	global_load_dwordx4 v[112:115], v[160:161], off offset:-4096
	global_load_dwordx4 v[116:119], v[160:161], off
	global_load_dwordx4 v[120:123], v[162:163], off
	global_load_dwordx4 v[124:127], v[164:165], off
	v_lshl_add_u64 v[160:161], v[160:161], 0, s[14:15]
	v_lshl_add_u64 v[162:163], v[162:163], 0, s[14:15]
	v_lshl_add_u64 v[164:165], v[164:165], 0, s[14:15]
	v_pk_mul_f32 v[48:49], v[136:137], v[8:9]
	v_pk_fma_f32 v[48:49], v[128:129], v[0:1], v[48:49]
	v_pk_fma_f32 v[48:49], v[144:145], v[16:17], v[48:49]
	v_pk_add_f32 v[48:49], v[152:153], v[48:49]
	v_pk_mul_f32 v[56:57], v[48:49], v[24:25]
	v_pk_mul_f32 v[50:51], v[138:139], v[10:11]
	v_pk_fma_f32 v[50:51], v[130:131], v[2:3], v[50:51]
	v_pk_fma_f32 v[50:51], v[146:147], v[18:19], v[50:51]
	v_pk_add_f32 v[50:51], v[154:155], v[50:51]
	v_pk_mul_f32 v[58:59], v[50:51], v[26:27]
	v_pk_mul_f32 v[52:53], v[140:141], v[12:13]
	v_pk_fma_f32 v[52:53], v[132:133], v[4:5], v[52:53]
	v_pk_fma_f32 v[52:53], v[148:149], v[20:21], v[52:53]
	v_pk_add_f32 v[52:53], v[156:157], v[52:53]
	v_pk_mul_f32 v[60:61], v[52:53], v[28:29]
	v_pk_mul_f32 v[54:55], v[142:143], v[14:15]
	v_pk_fma_f32 v[54:55], v[134:135], v[6:7], v[54:55]
	v_pk_fma_f32 v[54:55], v[150:151], v[22:23], v[54:55]
	v_pk_add_f32 v[54:55], v[158:159], v[54:55]
	v_pk_mul_f32 v[62:63], v[54:55], v[30:31]
	v_cvt_pk_bf16_f32 v44, v56, v57
	v_cvt_pk_bf16_f32 v45, v58, v59
	v_cvt_pk_bf16_f32 v46, v60, v61
	v_cvt_pk_bf16_f32 v47, v62, v63
	global_store_dwordx4 v[166:167], v[44:47], off
	v_lshl_add_u64 v[166:167], v[166:167], 0, s[14:15]
	s_addk_i32 s4, 0x200
	s_branch .Lcv_loop
.Lcv_done:
	s_waitcnt vmcnt(0)
	s_mov_b64 s[38:39], 0x800
	s_branch .LBB0_379

; __global__ void __launch_bounds__(512, 2) fwd_kernel(const Args a) {
;     ...
;                     if (!lat && nks > 0) {
;                         f32x4 ps[8];
; #pragma unroll
;                         for (int j = 0; j < 8; ++j) ps[j] = (f32x4){0.f, 0.f, 0.f, 0.f};
; #pragma unroll 2
;                         for (int kc = 0; kc < nks; ++kc) { const f32x4* pp = (const f32x4*)(PARTb + (size_t)kc * MC * D + (size_t)(m - ML) * D);
; #pragma unroll
;                             for (int j = 0; j < 8; ++j) ps[j] += pp[64 * j + lane]; }
.LBB0_452:
	s_mov_b32 s14, 0xffbff000
	v_add_co_u32_e32 v190, vcc, s14, v96
	s_mov_b32 s14, 0xffc00000
	s_nop 0
	v_addc_co_u32_e32 v191, vcc, -1, v97, vcc
	v_add_co_u32_e32 v192, vcc, s14, v96
	s_nop 1
	v_addc_co_u32_e32 v193, vcc, -1, v97, vcc
	v_add_co_u32_e32 v194, vcc, s95, v96
	s_nop 1
	v_addc_co_u32_e32 v195, vcc, -1, v97, vcc
	global_load_dwordx4 v[112:115], v[190:191], off offset:-3072
	global_load_dwordx4 v[116:119], v[190:191], off offset:-2048
	global_load_dwordx4 v[120:123], v[190:191], off offset:-1024
	global_load_dwordx4 v[124:127], v[192:193], off offset:-4096
	global_load_dwordx4 v[128:131], v[192:193], off offset:-3072
	global_load_dwordx4 v[132:135], v[192:193], off offset:-2048
	global_load_dwordx4 v[136:139], v[192:193], off offset:-1024
	global_load_dwordx4 v[140:143], v[192:193], off
	global_load_dwordx4 v[144:147], v[194:195], off offset:-3072
	global_load_dwordx4 v[148:151], v[194:195], off offset:-2048
	global_load_dwordx4 v[152:155], v[194:195], off offset:-1024
	global_load_dwordx4 v[156:159], v[96:97], off offset:-4096
	global_load_dwordx4 v[160:163], v[96:97], off offset:-3072
	global_load_dwordx4 v[164:167], v[96:97], off offset:-2048
	global_load_dwordx4 v[168:171], v[96:97], off offset:-1024
	global_load_dwordx4 v[172:175], v[96:97], off
	s_add_i32 s4, s4, 2
	s_mov_b64 s[34:35], 0x800000
	v_lshl_add_u64 v[96:97], v[96:97], 0, s[34:35]
	s_waitcnt vmcnt(8)
	v_pk_add_f32 v[92:93], v[92:93], v[112:113]
	v_pk_add_f32 v[94:95], v[94:95], v[114:115]
	v_pk_add_f32 v[88:89], v[88:89], v[116:117]
	v_pk_add_f32 v[90:91], v[90:91], v[118:119]
	v_pk_add_f32 v[84:85], v[84:85], v[120:121]
	v_pk_add_f32 v[86:87], v[86:87], v[122:123]
	v_pk_add_f32 v[70:71], v[70:71], v[124:125]
	v_pk_add_f32 v[72:73], v[72:73], v[126:127]
	v_pk_add_f32 v[80:81], v[80:81], v[128:129]
	v_pk_add_f32 v[82:83], v[82:83], v[130:131]
	v_pk_add_f32 v[76:77], v[76:77], v[132:133]
	v_pk_add_f32 v[78:79], v[78:79], v[134:135]
	v_pk_add_f32 v[74:75], v[74:75], v[136:137]
	v_pk_add_f32 v[68:69], v[68:69], v[138:139]
	v_pk_add_f32 v[64:65], v[64:65], v[140:141]
	v_pk_add_f32 v[66:67], v[66:67], v[142:143]
	s_waitcnt vmcnt(0)
	v_pk_add_f32 v[92:93], v[92:93], v[144:145]
	v_pk_add_f32 v[94:95], v[94:95], v[146:147]
	v_pk_add_f32 v[88:89], v[88:89], v[148:149]
	v_pk_add_f32 v[90:91], v[90:91], v[150:151]
	v_pk_add_f32 v[84:85], v[84:85], v[152:153]
	v_pk_add_f32 v[86:87], v[86:87], v[154:155]
	v_pk_add_f32 v[70:71], v[70:71], v[156:157]
	v_pk_add_f32 v[72:73], v[72:73], v[158:159]
	v_pk_add_f32 v[80:81], v[80:81], v[160:161]
	v_pk_add_f32 v[82:83], v[82:83], v[162:163]
	v_pk_add_f32 v[76:77], v[76:77], v[164:165]
	v_pk_add_f32 v[78:79], v[78:79], v[166:167]
	v_pk_add_f32 v[74:75], v[74:75], v[168:169]
	v_pk_add_f32 v[68:69], v[68:69], v[170:171]
	v_pk_add_f32 v[64:65], v[64:65], v[172:173]
	v_pk_add_f32 v[66:67], v[66:67], v[174:175]
	s_cmp_eq_u32 s44, s4
	s_cbranch_scc0 .LBB0_452
	s_andn2_b64 vcc, exec, s[30:31]
	s_cbranch_vccnz .LBB0_455
	s_lshl_b32 s4, s44, 22
	s_add_u32 s14, s62, s0
	s_addc_u32 s15, s63, s1
	s_add_u32 s34, s14, s4
	s_addc_u32 s35, s15, 0
	v_lshl_add_u64 v[96:97], s[34:35], 0, v[176:177]
	s_movk_i32 s4, 0x1000
	v_add_co_u32_e32 v96, vcc, s4, v96
	global_load_dwordx4 v[112:115], v176, s[34:35]
	global_load_dwordx4 v[116:119], v176, s[34:35] offset:1024
	global_load_dwordx4 v[120:123], v176, s[34:35] offset:2048
	global_load_dwordx4 v[124:127], v176, s[34:35] offset:3072
	v_addc_co_u32_e32 v97, vcc, 0, v97, vcc
	global_load_dwordx4 v[128:131], v[96:97], off
	global_load_dwordx4 v[132:135], v[96:97], off offset:1024
	global_load_dwordx4 v[136:139], v[96:97], off offset:2048
	global_load_dwordx4 v[140:143], v[96:97], off offset:3072
	s_waitcnt vmcnt(0)
	v_pk_add_f32 v[94:95], v[94:95], v[114:115]
	v_pk_add_f32 v[92:93], v[92:93], v[112:113]
	v_pk_add_f32 v[90:91], v[90:91], v[118:119]
	v_pk_add_f32 v[88:89], v[88:89], v[116:117]
	v_pk_add_f32 v[86:87], v[86:87], v[122:123]
	v_pk_add_f32 v[84:85], v[84:85], v[120:121]
	v_pk_add_f32 v[72:73], v[72:73], v[126:127]
	v_pk_add_f32 v[70:71], v[70:71], v[124:125]
	v_pk_add_f32 v[82:83], v[82:83], v[130:131]
	v_pk_add_f32 v[80:81], v[80:81], v[128:129]
	v_pk_add_f32 v[78:79], v[78:79], v[134:135]
	v_pk_add_f32 v[76:77], v[76:77], v[132:133]
	v_pk_add_f32 v[68:69], v[68:69], v[138:139]
	v_pk_add_f32 v[74:75], v[74:75], v[136:137]
	v_pk_add_f32 v[66:67], v[66:67], v[142:143]
	v_pk_add_f32 v[64:65], v[64:65], v[140:141]
